# select: DPP row_shr/row_bcast wave scans instead of 6-hop ds_bpermute scans
# speedup vs baseline: 1.0181x; 1.0031x over previous
.Lsel_cv_next7:
.Lsel_cv_done:
	v_max_u32_e32 v137, v137, v151
	s_nop 1
	v_max_u32_dpp v137, v137, v137 row_shr:1 row_mask:0xf bank_mask:0xf
	s_nop 1
	v_max_u32_dpp v137, v137, v137 row_shr:2 row_mask:0xf bank_mask:0xf
	s_nop 1
	v_max_u32_dpp v137, v137, v137 row_shr:4 row_mask:0xf bank_mask:0xf
	s_nop 1
	v_max_u32_dpp v137, v137, v137 row_shr:8 row_mask:0xf bank_mask:0xf
	s_nop 1
	v_max_u32_dpp v137, v137, v137 row_bcast:15 row_mask:0xa bank_mask:0xf
	s_nop 1
	v_max_u32_dpp v137, v137, v137 row_bcast:31 row_mask:0xc bank_mask:0xf
	s_nop 0
	v_readlane_b32 s86, v137, 63
	s_add_u32 s86, s86, 1
	s_movk_i32 s56, 0x100
	s_mov_b32 s57, 0
	s_mov_b32 s87, 21
	s_mov_b32 s88, 0

.Lsel_hist_done:
	s_waitcnt lgkmcnt(0)
	v_lshl_add_u32 v140, v131, 7, v136
	v_mov_b32_e32 v141, 0
	ds_read_b128 v[240:243], v140 offset:0
	ds_read_b128 v[244:247], v140 offset:16
	s_waitcnt lgkmcnt(0)
	v_add3_u32 v141, v141, v240, v241
	v_add3_u32 v141, v141, v242, v243
	v_add3_u32 v141, v141, v244, v245
	v_add3_u32 v141, v141, v246, v247
	ds_read_b128 v[240:243], v140 offset:32
	ds_read_b128 v[244:247], v140 offset:48
	s_waitcnt lgkmcnt(0)
	v_add3_u32 v141, v141, v240, v241
	v_add3_u32 v141, v141, v242, v243
	v_add3_u32 v141, v141, v244, v245
	v_add3_u32 v141, v141, v246, v247
	ds_read_b128 v[240:243], v140 offset:64
	ds_read_b128 v[244:247], v140 offset:80
	s_waitcnt lgkmcnt(0)
	v_add3_u32 v141, v141, v240, v241
	v_add3_u32 v141, v141, v242, v243
	v_add3_u32 v141, v141, v244, v245
	v_add3_u32 v141, v141, v246, v247
	ds_read_b128 v[240:243], v140 offset:96
	ds_read_b128 v[244:247], v140 offset:112
	s_waitcnt lgkmcnt(0)
	v_add3_u32 v141, v141, v240, v241
	v_add3_u32 v141, v141, v242, v243
	v_add3_u32 v141, v141, v244, v245
	v_add3_u32 v141, v141, v246, v247
	v_mov_b32_e32 v142, v141
	s_nop 1
	v_add_u32_dpp v142, v142, v142 row_shr:1 row_mask:0xf bank_mask:0xf
	s_nop 1
	v_add_u32_dpp v142, v142, v142 row_shr:2 row_mask:0xf bank_mask:0xf
	s_nop 1
	v_add_u32_dpp v142, v142, v142 row_shr:4 row_mask:0xf bank_mask:0xf
	s_nop 1
	v_add_u32_dpp v142, v142, v142 row_shr:8 row_mask:0xf bank_mask:0xf
	s_nop 1
	v_add_u32_dpp v142, v142, v142 row_bcast:15 row_mask:0xa bank_mask:0xf
	s_nop 1
	v_add_u32_dpp v142, v142, v142 row_bcast:31 row_mask:0xc bank_mask:0xf
	v_sub_u32_e32 v242, v142, v141
	v_cmp_gt_u32_e64 s[52:53], s56, v242
	v_cmp_le_u32_e64 s[54:55], s56, v142
	s_nop 1
	s_and_b64 s[52:53], s[52:53], s[54:55]
	s_ff1_i32_b64 s89, s[52:53]
	s_nop 3
	v_readlane_b32 s93, v242, s89
	s_sub_u32 s56, s56, s93
	s_lshl_b32 s93, s89, 7
	v_add3_u32 v140, v136, s93, v133
	ds_read_b32 v143, v140
	s_mov_b32 s90, 0
	s_waitcnt lgkmcnt(0)
	v_readlane_b32 s91, v143, 0
	s_add_u32 s90, s90, s91
	s_cmp_ge_u32 s90, s56
	s_cbranch_scc1 .Lsel_f0
	v_readlane_b32 s91, v143, 1
	s_add_u32 s90, s90, s91
	s_cmp_ge_u32 s90, s56
	s_cbranch_scc1 .Lsel_f1
	v_readlane_b32 s91, v143, 2
	s_add_u32 s90, s90, s91
	s_cmp_ge_u32 s90, s56
	s_cbranch_scc1 .Lsel_f2
	v_readlane_b32 s91, v143, 3
	s_add_u32 s90, s90, s91
	s_cmp_ge_u32 s90, s56
	s_cbranch_scc1 .Lsel_f3
	v_readlane_b32 s91, v143, 4
	s_add_u32 s90, s90, s91
	s_cmp_ge_u32 s90, s56
	s_cbranch_scc1 .Lsel_f4
	v_readlane_b32 s91, v143, 5
	s_add_u32 s90, s90, s91
	s_cmp_ge_u32 s90, s56
	s_cbranch_scc1 .Lsel_f5
	v_readlane_b32 s91, v143, 6
	s_add_u32 s90, s90, s91
	s_cmp_ge_u32 s90, s56
	s_cbranch_scc1 .Lsel_f6
	v_readlane_b32 s91, v143, 7
	s_add_u32 s90, s90, s91
	s_cmp_ge_u32 s90, s56
	s_cbranch_scc1 .Lsel_f7
	v_readlane_b32 s91, v143, 8
	s_add_u32 s90, s90, s91
	s_cmp_ge_u32 s90, s56
	s_cbranch_scc1 .Lsel_f8
	v_readlane_b32 s91, v143, 9
	s_add_u32 s90, s90, s91
	s_cmp_ge_u32 s90, s56
	s_cbranch_scc1 .Lsel_f9
	v_readlane_b32 s91, v143, 10
	s_add_u32 s90, s90, s91
	s_cmp_ge_u32 s90, s56
	s_cbranch_scc1 .Lsel_f10
	v_readlane_b32 s91, v143, 11
	s_add_u32 s90, s90, s91
	s_cmp_ge_u32 s90, s56
	s_cbranch_scc1 .Lsel_f11
	v_readlane_b32 s91, v143, 12
	s_add_u32 s90, s90, s91
	s_cmp_ge_u32 s90, s56
	s_cbranch_scc1 .Lsel_f12
	v_readlane_b32 s91, v143, 13
	s_add_u32 s90, s90, s91
	s_cmp_ge_u32 s90, s56
	s_cbranch_scc1 .Lsel_f13
	v_readlane_b32 s91, v143, 14
	s_add_u32 s90, s90, s91
	s_cmp_ge_u32 s90, s56
	s_cbranch_scc1 .Lsel_f14
	v_readlane_b32 s91, v143, 15
	s_add_u32 s90, s90, s91
	s_cmp_ge_u32 s90, s56
	s_cbranch_scc1 .Lsel_f15
	v_readlane_b32 s91, v143, 16
	s_add_u32 s90, s90, s91
	s_cmp_ge_u32 s90, s56
	s_cbranch_scc1 .Lsel_f16
	v_readlane_b32 s91, v143, 17
	s_add_u32 s90, s90, s91
	s_cmp_ge_u32 s90, s56
	s_cbranch_scc1 .Lsel_f17
	v_readlane_b32 s91, v143, 18
	s_add_u32 s90, s90, s91
	s_cmp_ge_u32 s90, s56
	s_cbranch_scc1 .Lsel_f18
	v_readlane_b32 s91, v143, 19
	s_add_u32 s90, s90, s91
	s_cmp_ge_u32 s90, s56
	s_cbranch_scc1 .Lsel_f19
	v_readlane_b32 s91, v143, 20
	s_add_u32 s90, s90, s91
	s_cmp_ge_u32 s90, s56
	s_cbranch_scc1 .Lsel_f20
	v_readlane_b32 s91, v143, 21
	s_add_u32 s90, s90, s91
	s_cmp_ge_u32 s90, s56
	s_cbranch_scc1 .Lsel_f21
	v_readlane_b32 s91, v143, 22
	s_add_u32 s90, s90, s91
	s_cmp_ge_u32 s90, s56
	s_cbranch_scc1 .Lsel_f22
	v_readlane_b32 s91, v143, 23
	s_add_u32 s90, s90, s91
	s_cmp_ge_u32 s90, s56
	s_cbranch_scc1 .Lsel_f23
	v_readlane_b32 s91, v143, 24
	s_add_u32 s90, s90, s91
	s_cmp_ge_u32 s90, s56
	s_cbranch_scc1 .Lsel_f24
	v_readlane_b32 s91, v143, 25
	s_add_u32 s90, s90, s91
	s_cmp_ge_u32 s90, s56
	s_cbranch_scc1 .Lsel_f25
	v_readlane_b32 s91, v143, 26
	s_add_u32 s90, s90, s91
	s_cmp_ge_u32 s90, s56
	s_cbranch_scc1 .Lsel_f26
	v_readlane_b32 s91, v143, 27
	s_add_u32 s90, s90, s91
	s_cmp_ge_u32 s90, s56
	s_cbranch_scc1 .Lsel_f27
	v_readlane_b32 s91, v143, 28
	s_add_u32 s90, s90, s91
	s_cmp_ge_u32 s90, s56
	s_cbranch_scc1 .Lsel_f28
	v_readlane_b32 s91, v143, 29
	s_add_u32 s90, s90, s91
	s_cmp_ge_u32 s90, s56
	s_cbranch_scc1 .Lsel_f29
	v_readlane_b32 s91, v143, 30
	s_add_u32 s90, s90, s91
	s_cmp_ge_u32 s90, s56
	s_cbranch_scc1 .Lsel_f30
	v_readlane_b32 s91, v143, 31
	s_add_u32 s90, s90, s91
	s_cmp_ge_u32 s90, s56
	s_cbranch_scc1 .Lsel_f31
